# X3 and H3 mixer epilogues: gate loads batched before one wait instead of per-element load-wait-store
# speedup vs baseline: 1.0163x; 1.0048x over previous
; __device__ __forceinline__ float bf2f(unsigned short b) { return __uint_as_float(((unsigned)b) << 16); }
; __device__ __forceinline__ void phase_h3(const Args& a, LAS unsigned char* lds, int G) {
;     ...
;         float rn[4];
; #pragma unroll
;         for (int r = 0; r < 4; ++r) { float s = 0.f;
; #pragma unroll
;             for (int n = 0; n < 8; ++n) s += o[n][r] * o[n][r];
;             s += __shfl_xor(s, 1); s += __shfl_xor(s, 2); s += __shfl_xor(s, 4); s += __shfl_xor(s, 8);
;             rn[r] = __builtin_amdgcn_rsqf(s * (1.0f / HD) + RMS_EPS); }
; #pragma unroll
;         for (int n = 0; n < 8; ++n) { const float on = a.hg_onorm[16 * n + i16];
; #pragma unroll
;             for (int r = 0; r < 4; ++r) { const size_t off = (size_t)(R0 + 16 * I + 4 * g + r) * DM + hb + 16 * n + i16;
;                 const float val = o[n][r] * rn[r] * on * bf2f(GBp[off]); OG[off] = (bf16_t)(cvtpk(val, 0.f) & 0xffffu); } }
.LBB0_1117:
	v_or_b32_e32 v88, s62, v143
	v_mov_b32_e32 v85, s31
	v_or_b32_e32 v84, s30, v98
	global_load_dword v64, v[110:111], off
	global_load_dword v65, v[110:111], off offset:64
	global_load_dword v66, v[110:111], off offset:128
	global_load_dword v67, v[110:111], off offset:192
	global_load_dword v68, v[110:111], off offset:256
	global_load_dword v69, v[110:111], off offset:320
	global_load_dword v70, v[110:111], off offset:384
	global_load_dword v71, v[110:111], off offset:448
	v_mov_b32_e32 v86, v88
	v_ashrrev_i32_e32 v87, 31, v86
	v_lshlrev_b64 v[86:87], 11, v[86:87]
	v_lshl_add_u64 v[86:87], v[86:87], 0, v[84:85]
	v_lshlrev_b64 v[86:87], 1, v[86:87]
	v_lshl_add_u64 v[86:87], s[16:17], 0, v[86:87]
	global_load_ushort v32, v[86:87], off
	global_load_ushort v36, v[86:87], off offset:32
	global_load_ushort v40, v[86:87], off offset:64
	global_load_ushort v44, v[86:87], off offset:96
	global_load_ushort v48, v[86:87], off offset:128
	global_load_ushort v52, v[86:87], off offset:160
	global_load_ushort v56, v[86:87], off offset:192
	global_load_ushort v60, v[86:87], off offset:224
	v_or_b32_e32 v86, 1, v88
	v_ashrrev_i32_e32 v87, 31, v86
	v_lshlrev_b64 v[86:87], 11, v[86:87]
	v_lshl_add_u64 v[86:87], v[86:87], 0, v[84:85]
	v_lshlrev_b64 v[86:87], 1, v[86:87]
	v_lshl_add_u64 v[86:87], s[16:17], 0, v[86:87]
	global_load_ushort v33, v[86:87], off
	global_load_ushort v37, v[86:87], off offset:32
	global_load_ushort v41, v[86:87], off offset:64
	global_load_ushort v45, v[86:87], off offset:96
	global_load_ushort v49, v[86:87], off offset:128
	global_load_ushort v53, v[86:87], off offset:160
	global_load_ushort v57, v[86:87], off offset:192
	global_load_ushort v61, v[86:87], off offset:224
	v_or_b32_e32 v86, 2, v88
	v_ashrrev_i32_e32 v87, 31, v86
	v_lshlrev_b64 v[86:87], 11, v[86:87]
	v_lshl_add_u64 v[86:87], v[86:87], 0, v[84:85]
	v_lshlrev_b64 v[86:87], 1, v[86:87]
	v_lshl_add_u64 v[86:87], s[16:17], 0, v[86:87]
	global_load_ushort v34, v[86:87], off
	global_load_ushort v38, v[86:87], off offset:32
	global_load_ushort v42, v[86:87], off offset:64
	global_load_ushort v46, v[86:87], off offset:96
	global_load_ushort v50, v[86:87], off offset:128
	global_load_ushort v54, v[86:87], off offset:160
	global_load_ushort v58, v[86:87], off offset:192
	global_load_ushort v62, v[86:87], off offset:224
	v_or_b32_e32 v86, 3, v88
	v_ashrrev_i32_e32 v87, 31, v86
	v_lshlrev_b64 v[86:87], 11, v[86:87]
	v_lshl_add_u64 v[86:87], v[86:87], 0, v[84:85]
	v_lshlrev_b64 v[86:87], 1, v[86:87]
	v_lshl_add_u64 v[86:87], s[16:17], 0, v[86:87]
	global_load_ushort v35, v[86:87], off
	global_load_ushort v39, v[86:87], off offset:32
	global_load_ushort v43, v[86:87], off offset:64
	global_load_ushort v47, v[86:87], off offset:96
	global_load_ushort v51, v[86:87], off offset:128
	global_load_ushort v55, v[86:87], off offset:160
	global_load_ushort v59, v[86:87], off offset:192
	global_load_ushort v63, v[86:87], off offset:224
	v_xor_b32_e32 v72, 1, v152
	v_lshlrev_b32_e32 v72, 2, v72
	v_xor_b32_e32 v73, 2, v152
	v_lshlrev_b32_e32 v73, 2, v73
	v_xor_b32_e32 v74, 4, v152
	v_lshlrev_b32_e32 v74, 2, v74
	v_xor_b32_e32 v75, 8, v152
	v_lshlrev_b32_e32 v75, 2, v75
	v_mul_f32_e32 v76, v28, v28
	v_fmac_f32_e32 v76, v24, v24
	v_fmac_f32_e32 v76, v20, v20
	v_fmac_f32_e32 v76, v16, v16
	v_fmac_f32_e32 v76, v12, v12
	v_fmac_f32_e32 v76, v8, v8
	v_fmac_f32_e32 v76, v4, v4
	v_fmac_f32_e32 v76, v0, v0
	v_mul_f32_e32 v77, v29, v29
	v_fmac_f32_e32 v77, v25, v25
	v_fmac_f32_e32 v77, v21, v21
	v_fmac_f32_e32 v77, v17, v17
	v_fmac_f32_e32 v77, v13, v13
	v_fmac_f32_e32 v77, v9, v9
	v_fmac_f32_e32 v77, v5, v5
	v_fmac_f32_e32 v77, v1, v1
	v_mul_f32_e32 v78, v30, v30
	v_fmac_f32_e32 v78, v26, v26
	v_fmac_f32_e32 v78, v22, v22
	v_fmac_f32_e32 v78, v18, v18
	v_fmac_f32_e32 v78, v14, v14
	v_fmac_f32_e32 v78, v10, v10
	v_fmac_f32_e32 v78, v6, v6
	v_fmac_f32_e32 v78, v2, v2
	v_mul_f32_e32 v79, v31, v31
	v_fmac_f32_e32 v79, v27, v27
	v_fmac_f32_e32 v79, v23, v23
	v_fmac_f32_e32 v79, v19, v19
	v_fmac_f32_e32 v79, v15, v15
	v_fmac_f32_e32 v79, v11, v11
	v_fmac_f32_e32 v79, v7, v7
	v_fmac_f32_e32 v79, v3, v3
	ds_bpermute_b32 v80, v72, v76
	ds_bpermute_b32 v81, v72, v77
	ds_bpermute_b32 v82, v72, v78
	ds_bpermute_b32 v83, v72, v79
	s_waitcnt lgkmcnt(0)
	v_add_f32_e32 v76, v76, v80
	v_add_f32_e32 v77, v77, v81
	v_add_f32_e32 v78, v78, v82
	v_add_f32_e32 v79, v79, v83
	ds_bpermute_b32 v80, v73, v76
	ds_bpermute_b32 v81, v73, v77
	ds_bpermute_b32 v82, v73, v78
	ds_bpermute_b32 v83, v73, v79
	s_waitcnt lgkmcnt(0)
	v_add_f32_e32 v76, v76, v80
	v_add_f32_e32 v77, v77, v81
	v_add_f32_e32 v78, v78, v82
	v_add_f32_e32 v79, v79, v83
	ds_bpermute_b32 v80, v74, v76
	ds_bpermute_b32 v81, v74, v77
	ds_bpermute_b32 v82, v74, v78
	ds_bpermute_b32 v83, v74, v79
	s_waitcnt lgkmcnt(0)
	v_add_f32_e32 v76, v76, v80
	v_add_f32_e32 v77, v77, v81
	v_add_f32_e32 v78, v78, v82
	v_add_f32_e32 v79, v79, v83
	ds_bpermute_b32 v80, v75, v76
	ds_bpermute_b32 v81, v75, v77
	ds_bpermute_b32 v82, v75, v78
	ds_bpermute_b32 v83, v75, v79
	s_waitcnt lgkmcnt(0)
; __device__ __forceinline__ float bf2f(unsigned short b) { return __uint_as_float(((unsigned)b) << 16); }
; __device__ __forceinline__ void phase_h3(const Args& a, LAS unsigned char* lds, int G) {
;     ...
;         for (int r = 0; r < 4; ++r) { float s = 0.f;
; #pragma unroll
;             for (int n = 0; n < 8; ++n) s += o[n][r] * o[n][r];
;             s += __shfl_xor(s, 1); s += __shfl_xor(s, 2); s += __shfl_xor(s, 4); s += __shfl_xor(s, 8);
;             rn[r] = __builtin_amdgcn_rsqf(s * (1.0f / HD) + RMS_EPS); }
; #pragma unroll
;         for (int n = 0; n < 8; ++n) { const float on = a.hg_onorm[16 * n + i16];
; #pragma unroll
;             for (int r = 0; r < 4; ++r) { const size_t off = (size_t)(R0 + 16 * I + 4 * g + r) * DM + hb + 16 * n + i16;
;                 const float val = o[n][r] * rn[r] * on * bf2f(GBp[off]); OG[off] = (bf16_t)(cvtpk(val, 0.f) & 0xffffu); } }
	v_add_f32_e32 v76, v76, v80
	v_add_f32_e32 v77, v77, v81
	v_add_f32_e32 v78, v78, v82
	v_add_f32_e32 v79, v79, v83
	v_fmamk_f32 v76, v76, 0x3c000000, v146
	v_fmamk_f32 v77, v77, 0x3c000000, v146
	v_fmamk_f32 v78, v78, 0x3c000000, v146
	v_fmamk_f32 v79, v79, 0x3c000000, v146
	v_rsq_f32_e32 v76, v76
	v_rsq_f32_e32 v77, v77
	v_rsq_f32_e32 v78, v78
	v_rsq_f32_e32 v79, v79
	s_nop 0
	v_mul_f32_e32 v28, v28, v76
	v_mul_f32_e32 v24, v24, v76
	v_mul_f32_e32 v20, v20, v76
	v_mul_f32_e32 v16, v16, v76
	v_mul_f32_e32 v12, v12, v76
	v_mul_f32_e32 v8, v8, v76
	v_mul_f32_e32 v4, v4, v76
	v_mul_f32_e32 v0, v0, v76
	v_mul_f32_e32 v29, v29, v77
	v_mul_f32_e32 v25, v25, v77
	v_mul_f32_e32 v21, v21, v77
	v_mul_f32_e32 v17, v17, v77
	v_mul_f32_e32 v13, v13, v77
	v_mul_f32_e32 v9, v9, v77
	v_mul_f32_e32 v5, v5, v77
	v_mul_f32_e32 v1, v1, v77
	v_mul_f32_e32 v30, v30, v78
	v_mul_f32_e32 v26, v26, v78
	v_mul_f32_e32 v22, v22, v78
	v_mul_f32_e32 v18, v18, v78
	v_mul_f32_e32 v14, v14, v78
	v_mul_f32_e32 v10, v10, v78
	v_mul_f32_e32 v6, v6, v78
	v_mul_f32_e32 v2, v2, v78
	v_mul_f32_e32 v31, v31, v79
	v_mul_f32_e32 v27, v27, v79
	v_mul_f32_e32 v23, v23, v79
	v_mul_f32_e32 v19, v19, v79
	v_mul_f32_e32 v15, v15, v79
	v_mul_f32_e32 v11, v11, v79
	v_mul_f32_e32 v7, v7, v79
	v_mul_f32_e32 v3, v3, v79
	s_waitcnt vmcnt(0)
; __device__ __forceinline__ float bf2f(unsigned short b) { return __uint_as_float(((unsigned)b) << 16); }
; __device__ __forceinline__ void phase_h3(const Args& a, LAS unsigned char* lds, int G) {
;     ...
;         for (int n = 0; n < 8; ++n) { const float on = a.hg_onorm[16 * n + i16];
; #pragma unroll
;             for (int r = 0; r < 4; ++r) { const size_t off = (size_t)(R0 + 16 * I + 4 * g + r) * DM + hb + 16 * n + i16;
;                 const float val = o[n][r] * rn[r] * on * bf2f(GBp[off]); OG[off] = (bf16_t)(cvtpk(val, 0.f) & 0xffffu); } }
	v_mul_f32_e32 v28, v28, v64
	v_mul_f32_e32 v24, v24, v65
	v_mul_f32_e32 v20, v20, v66
	v_mul_f32_e32 v16, v16, v67
	v_mul_f32_e32 v12, v12, v68
	v_mul_f32_e32 v8, v8, v69
	v_mul_f32_e32 v4, v4, v70
	v_mul_f32_e32 v0, v0, v71
	v_mul_f32_e32 v29, v29, v64
	v_mul_f32_e32 v25, v25, v65
	v_mul_f32_e32 v21, v21, v66
	v_mul_f32_e32 v17, v17, v67
	v_mul_f32_e32 v13, v13, v68
	v_mul_f32_e32 v9, v9, v69
	v_mul_f32_e32 v5, v5, v70
	v_mul_f32_e32 v1, v1, v71
	v_mul_f32_e32 v30, v30, v64
	v_mul_f32_e32 v26, v26, v65
	v_mul_f32_e32 v22, v22, v66
	v_mul_f32_e32 v18, v18, v67
	v_mul_f32_e32 v14, v14, v68
	v_mul_f32_e32 v10, v10, v69
	v_mul_f32_e32 v6, v6, v70
	v_mul_f32_e32 v2, v2, v71
	v_mul_f32_e32 v31, v31, v64
	v_mul_f32_e32 v27, v27, v65
	v_mul_f32_e32 v23, v23, v66
	v_mul_f32_e32 v19, v19, v67
	v_mul_f32_e32 v15, v15, v68
	v_mul_f32_e32 v11, v11, v69
	v_mul_f32_e32 v7, v7, v70
	v_mul_f32_e32 v3, v3, v71
	v_mov_b32_e32 v86, v88
	v_ashrrev_i32_e32 v87, 31, v86
	v_lshlrev_b64 v[86:87], 11, v[86:87]
	v_lshl_add_u64 v[86:87], v[86:87], 0, v[84:85]
	v_lshlrev_b64 v[86:87], 1, v[86:87]
	v_lshl_add_u64 v[86:87], s[18:19], 0, v[86:87]
	v_lshlrev_b32_e32 v32, 16, v32
	v_lshlrev_b32_e32 v36, 16, v36
	v_lshlrev_b32_e32 v40, 16, v40
	v_lshlrev_b32_e32 v44, 16, v44
	v_lshlrev_b32_e32 v48, 16, v48
	v_lshlrev_b32_e32 v52, 16, v52
	v_lshlrev_b32_e32 v56, 16, v56
	v_lshlrev_b32_e32 v60, 16, v60
	v_mul_f32_e32 v28, v28, v32
	v_mul_f32_e32 v24, v24, v36
	v_mul_f32_e32 v20, v20, v40
	v_mul_f32_e32 v16, v16, v44
	v_mul_f32_e32 v12, v12, v48
	v_mul_f32_e32 v8, v8, v52
	v_mul_f32_e32 v4, v4, v56
	v_mul_f32_e32 v0, v0, v60
	v_cvt_pk_bf16_f32 v28, v28, v28
	v_cvt_pk_bf16_f32 v24, v24, v24
	v_cvt_pk_bf16_f32 v20, v20, v20
	v_cvt_pk_bf16_f32 v16, v16, v16
	v_cvt_pk_bf16_f32 v12, v12, v12
	v_cvt_pk_bf16_f32 v8, v8, v8
	v_cvt_pk_bf16_f32 v4, v4, v4
	v_cvt_pk_bf16_f32 v0, v0, v0
	global_store_short v[86:87], v28, off
	global_store_short v[86:87], v24, off offset:32
	global_store_short v[86:87], v20, off offset:64
	global_store_short v[86:87], v16, off offset:96
	global_store_short v[86:87], v12, off offset:128
	global_store_short v[86:87], v8, off offset:160
	global_store_short v[86:87], v4, off offset:192
	global_store_short v[86:87], v0, off offset:224
	v_or_b32_e32 v86, 1, v88
	v_ashrrev_i32_e32 v87, 31, v86
	v_lshlrev_b64 v[86:87], 11, v[86:87]
	v_lshl_add_u64 v[86:87], v[86:87], 0, v[84:85]
	v_lshlrev_b64 v[86:87], 1, v[86:87]
	v_lshl_add_u64 v[86:87], s[18:19], 0, v[86:87]
	v_lshlrev_b32_e32 v33, 16, v33
	v_lshlrev_b32_e32 v37, 16, v37
	v_lshlrev_b32_e32 v41, 16, v41
	v_lshlrev_b32_e32 v45, 16, v45
	v_lshlrev_b32_e32 v49, 16, v49
	v_lshlrev_b32_e32 v53, 16, v53
	v_lshlrev_b32_e32 v57, 16, v57
	v_lshlrev_b32_e32 v61, 16, v61
	v_mul_f32_e32 v29, v29, v33
	v_mul_f32_e32 v25, v25, v37
	v_mul_f32_e32 v21, v21, v41
	v_mul_f32_e32 v17, v17, v45
	v_mul_f32_e32 v13, v13, v49
	v_mul_f32_e32 v9, v9, v53
	v_mul_f32_e32 v5, v5, v57
	v_mul_f32_e32 v1, v1, v61
	v_cvt_pk_bf16_f32 v29, v29, v29
	v_cvt_pk_bf16_f32 v25, v25, v25
	v_cvt_pk_bf16_f32 v21, v21, v21
	v_cvt_pk_bf16_f32 v17, v17, v17
	v_cvt_pk_bf16_f32 v13, v13, v13
	v_cvt_pk_bf16_f32 v9, v9, v9
	v_cvt_pk_bf16_f32 v5, v5, v5
	v_cvt_pk_bf16_f32 v1, v1, v1
	global_store_short v[86:87], v29, off
	global_store_short v[86:87], v25, off offset:32
	global_store_short v[86:87], v21, off offset:64
	global_store_short v[86:87], v17, off offset:96
	global_store_short v[86:87], v13, off offset:128
	global_store_short v[86:87], v9, off offset:160
	global_store_short v[86:87], v5, off offset:192
	global_store_short v[86:87], v1, off offset:224
	v_or_b32_e32 v86, 2, v88
	v_ashrrev_i32_e32 v87, 31, v86
	v_lshlrev_b64 v[86:87], 11, v[86:87]
	v_lshl_add_u64 v[86:87], v[86:87], 0, v[84:85]
	v_lshlrev_b64 v[86:87], 1, v[86:87]
	v_lshl_add_u64 v[86:87], s[18:19], 0, v[86:87]
	v_lshlrev_b32_e32 v34, 16, v34
	v_lshlrev_b32_e32 v38, 16, v38
	v_lshlrev_b32_e32 v42, 16, v42
	v_lshlrev_b32_e32 v46, 16, v46
	v_lshlrev_b32_e32 v50, 16, v50
	v_lshlrev_b32_e32 v54, 16, v54
	v_lshlrev_b32_e32 v58, 16, v58
	v_lshlrev_b32_e32 v62, 16, v62
	v_mul_f32_e32 v30, v30, v34
	v_mul_f32_e32 v26, v26, v38
	v_mul_f32_e32 v22, v22, v42
	v_mul_f32_e32 v18, v18, v46
	v_mul_f32_e32 v14, v14, v50
	v_mul_f32_e32 v10, v10, v54
	v_mul_f32_e32 v6, v6, v58
	v_mul_f32_e32 v2, v2, v62
	v_cvt_pk_bf16_f32 v30, v30, v30
	v_cvt_pk_bf16_f32 v26, v26, v26
	v_cvt_pk_bf16_f32 v22, v22, v22
	v_cvt_pk_bf16_f32 v18, v18, v18
	v_cvt_pk_bf16_f32 v14, v14, v14
	v_cvt_pk_bf16_f32 v10, v10, v10
	v_cvt_pk_bf16_f32 v6, v6, v6
	v_cvt_pk_bf16_f32 v2, v2, v2
	global_store_short v[86:87], v30, off
	global_store_short v[86:87], v26, off offset:32
	global_store_short v[86:87], v22, off offset:64
	global_store_short v[86:87], v18, off offset:96
	global_store_short v[86:87], v14, off offset:128
	global_store_short v[86:87], v10, off offset:160
	global_store_short v[86:87], v6, off offset:192
	global_store_short v[86:87], v2, off offset:224
	v_or_b32_e32 v86, 3, v88
	v_ashrrev_i32_e32 v87, 31, v86
	v_lshlrev_b64 v[86:87], 11, v[86:87]
	v_lshl_add_u64 v[86:87], v[86:87], 0, v[84:85]
	v_lshlrev_b64 v[86:87], 1, v[86:87]
	v_lshl_add_u64 v[86:87], s[18:19], 0, v[86:87]
	v_lshlrev_b32_e32 v35, 16, v35
	v_lshlrev_b32_e32 v39, 16, v39
	v_lshlrev_b32_e32 v43, 16, v43
	v_lshlrev_b32_e32 v47, 16, v47
	v_lshlrev_b32_e32 v51, 16, v51
	v_lshlrev_b32_e32 v55, 16, v55
	v_lshlrev_b32_e32 v59, 16, v59
	v_lshlrev_b32_e32 v63, 16, v63
	v_mul_f32_e32 v31, v31, v35
	v_mul_f32_e32 v27, v27, v39
	v_mul_f32_e32 v23, v23, v43
	v_mul_f32_e32 v19, v19, v47
	v_mul_f32_e32 v15, v15, v51
	v_mul_f32_e32 v11, v11, v55
	v_mul_f32_e32 v7, v7, v59
	v_mul_f32_e32 v3, v3, v63
	v_cvt_pk_bf16_f32 v31, v31, v31
	v_cvt_pk_bf16_f32 v27, v27, v27
	v_cvt_pk_bf16_f32 v23, v23, v23
	v_cvt_pk_bf16_f32 v19, v19, v19
	v_cvt_pk_bf16_f32 v15, v15, v15
	v_cvt_pk_bf16_f32 v11, v11, v11
	v_cvt_pk_bf16_f32 v7, v7, v7
	v_cvt_pk_bf16_f32 v3, v3, v3
	global_store_short v[86:87], v31, off
	global_store_short v[86:87], v27, off offset:32
	global_store_short v[86:87], v23, off offset:64
	global_store_short v[86:87], v19, off offset:96
	global_store_short v[86:87], v15, off offset:128
	global_store_short v[86:87], v11, off offset:160
	global_store_short v[86:87], v7, off offset:192
	global_store_short v[86:87], v3, off offset:224
